# v51: P4 state-pass state update issues its 3rd/4th kd^T fragment reads before the first MFMA of each block (as in P6)
# baseline (speedup 1.0000x reference)
; template <bool FULL, bool PARTIAL  > ...
;     ...
;             for (int g2 = 0; g2 < 4; ++g2) { float s4 = 0.f;
; #pragma unroll
;                 for (int e = 0; e < 4; ++e) { float la = log_sigmoid(bacc[4 * g2 + e]) * 0.0625f; if (PARTIAL) la = (32 * tt + 8 * g2 + 4 * h + e < nvalid) ? la : 0.f; bc[4 * g2 + e] = la; s4 += la; }
;                 sg[g2] = s4; }
; #pragma unroll
;             for (int g2 = 0; g2 < 4; ++g2) pg[g2] = __shfl_xor(sg[g2], 32);
;             float pre = 0.f;
; #pragma unroll
;             for (int g2 = 0; g2 < 4; ++g2) { float run = pre + (h ? pg[g2] : 0.f);
; #pragma unroll
;                 for (int e = 0; e < 4; ++e) { run += bc[4 * g2 + e]; bc[4 * g2 + e] = run; }
;                 pre += sg[g2] + pg[g2]; }
;             if (h == 0) CS[tt * 128 + kk] = pre;
;         }
;         __syncthreads();
;         const float offs = tt ? CS[kk] : 0.f, blast = CS[kk] + CS[128 + kk];
;         const float eblast = fast_exp(blast);
;         if (tt == 0 && h == 0) { EB[kk] = eblast; dsum += blast; }
;         {
;             LAS bf16_t* qs_e = opq(QS + (32 * tt + 4 * h) * QST + kk); LAS bf16_t* ks_e = qs_e + 64 * QST;
;             LAS bf16_t* kdt_w = opq(KdT + kk * TST + 32 * tt + 4 * h);
; #pragma unroll
;             for (int g2 = 0; g2 < 4; ++g2) {
;                 unsigned kdw[2];
; #pragma unroll
;                 for (int e = 0; e < 4; e += 2) {
;                     const int j = 4 * g2 + e, t0 = 8 * g2 + e;
;                     const float b0 = bc[j] + offs, b1 = bc[j + 1] + offs;
;                     const float k0 = bf2f(ks_e[t0 * QST]), k1 = bf2f(ks_e[(t0 + 1) * QST]);
;                     float e0 = 0.f, e1 = 0.f, r0, r1;
;                     if (FULL) { e0 = fast_exp(b0); e1 = fast_exp(b1); r0 = __builtin_amdgcn_rcpf(e0); r1 = __builtin_amdgcn_rcpf(e1); } else { r0 = fast_exp(-b0); r1 = fast_exp(-b1); }
;                     const float kt0 = k0 * r0, kt1 = k1 * r1;
;                     kdw[e >> 1] = cvtpk(kt0 * eblast, kt1 * eblast);
;                     if (FULL) {
;                         const float q0 = bf2f(qs_e[t0 * QST]), q1 = bf2f(qs_e[(t0 + 1) * QST]);
;                         qs_e[t0 * QST] = f2bf(q0 * e0); qs_e[(t0 + 1) * QST] = f2bf(q1 * e1);
;                         ks_e[t0 * QST] = f2bf(kt0); ks_e[(t0 + 1) * QST] = f2bf(kt1);
;                     }
;                 }
.LBB0_1043:
	s_or_b64 exec, exec, s[30:31]
	v_mul_f32_e32 v85, 0x3d800000, v116
	v_mul_f32_e32 v116, 0x3d800000, v149
	v_mul_f32_e32 v149, 0x3d800000, v150
	v_mul_f32_e32 v150, 0x3d800000, v151
	v_cndmask_b32_e64 v151, v84, 0, s[26:27]
	v_add_f32_e32 v84, 0, v157
	v_cndmask_b32_e64 v84, v84, 0, s[4:5]
	v_add_f32_e32 v84, v84, v85
	v_mul_f32_e32 v83, 0x3d800000, v83
	v_add_f32_e32 v85, v116, v84
	v_add_f32_e32 v116, v83, v85
	v_cndmask_b32_e64 v83, v155, 0, s[4:5]
	v_add_f32_e32 v83, v83, v158
	v_add_f32_e32 v150, v150, v83
	v_cndmask_b32_e64 v83, v154, 0, s[4:5]
	v_mul_f32_e32 v89, 0x3d800000, v89
	v_add_f32_e32 v83, v83, v156
	v_add_f32_e32 v154, v89, v83
	v_cndmask_b32_e64 v83, v97, 0, s[4:5]
	v_mul_f32_e32 v86, 0x3d800000, v86
	v_mul_f32_e32 v93, 0x3d800000, v93
	v_add_f32_e32 v83, v83, v153
	v_mov_b32_e32 v97, v120
	v_mul_f32_e32 v87, 0x3d800000, v87
	v_add_f32_e32 v152, v86, v150
	v_add_f32_e32 v93, v93, v83
	v_mov_b32_e32 v83, v136
	v_add_f32_e32 v155, v87, v152
	v_add_f32_e32 v84, v84, v151
	v_add_f32_e32 v85, v85, v151
	ds_read_u16 v86, v97 offset:17408
	ds_read_u16 v87, v97 offset:17680
	v_mul_f32_e32 v84, 0xbfb8aa3b, v84
	v_mul_f32_e32 v85, 0xbfb8aa3b, v85
	v_exp_f32_e32 v84, v84
	v_exp_f32_e32 v85, v85
	s_waitcnt lgkmcnt(0)
	v_lshlrev_b32_e32 v87, 16, v87
	v_lshlrev_b32_e32 v86, 16, v86
	v_add_f32_e32 v149, v149, v116
	v_pk_mul_f32 v[84:85], v[84:85], v[86:87]
	v_add_f32_e32 v87, v149, v151
	v_pk_mul_f32 v[84:85], v[82:83], v[84:85] op_sel_hi:[0,1]
	v_cvt_pk_bf16_f32 v84, v84, v85
	v_add_f32_e32 v85, v116, v151
	v_mul_f32_e32 v85, 0xbfb8aa3b, v85
	v_mul_f32_e32 v88, 0x3d800000, v88
	v_exp_f32_e32 v86, v85
	v_mul_f32_e32 v85, 0xbfb8aa3b, v87
	v_add_f32_e32 v157, v88, v155
	v_exp_f32_e32 v87, v85
	ds_read_u16 v85, v97 offset:17952
	ds_read_u16 v88, v97 offset:18224
	v_mul_f32_e32 v90, 0x3d800000, v90
	v_add_f32_e32 v90, v90, v154
	v_mul_f32_e32 v91, 0x3d800000, v91
	v_mul_f32_e32 v92, 0x3d800000, v92
	s_waitcnt lgkmcnt(0)
	v_lshlrev_b32_e32 v89, 16, v88
	v_lshlrev_b32_e32 v88, 16, v85
	v_pk_mul_f32 v[86:87], v[86:87], v[88:89]
	v_add_f32_e32 v91, v91, v90
	v_pk_mul_f32 v[86:87], v[82:83], v[86:87] op_sel_hi:[0,1]
	v_cvt_pk_bf16_f32 v85, v86, v87
	ds_write_b64 v83, v[84:85]
	v_add_f32_e32 v84, v150, v151
	v_add_f32_e32 v85, v152, v151
	ds_read_u16 v86, v97 offset:19584
	ds_read_u16 v87, v97 offset:19856
	v_mul_f32_e32 v84, 0xbfb8aa3b, v84
	v_mul_f32_e32 v85, 0xbfb8aa3b, v85
	v_exp_f32_e32 v84, v84
	v_exp_f32_e32 v85, v85
	s_waitcnt lgkmcnt(0)
	v_lshlrev_b32_e32 v87, 16, v87
	v_lshlrev_b32_e32 v86, 16, v86
	v_add_f32_e32 v92, v92, v91
	v_pk_mul_f32 v[84:85], v[84:85], v[86:87]
	v_add_f32_e32 v87, v157, v151
	v_pk_mul_f32 v[84:85], v[82:83], v[84:85] op_sel_hi:[0,1]
	v_cvt_pk_bf16_f32 v84, v84, v85
	v_add_f32_e32 v85, v155, v151
	v_mul_f32_e32 v85, 0xbfb8aa3b, v85
	v_exp_f32_e32 v86, v85
	v_mul_f32_e32 v85, 0xbfb8aa3b, v87
	v_exp_f32_e32 v87, v85
	ds_read_u16 v85, v97 offset:20128
	ds_read_u16 v88, v97 offset:20400
	v_mul_f32_e32 v94, 0x3d800000, v94
	v_add_f32_e32 v94, v94, v93
	v_mul_f32_e32 v95, 0x3d800000, v95
	v_mul_f32_e32 v96, 0x3d800000, v96
	s_waitcnt lgkmcnt(0)
	v_lshlrev_b32_e32 v89, 16, v88
	v_lshlrev_b32_e32 v88, 16, v85
	v_pk_mul_f32 v[86:87], v[86:87], v[88:89]
	v_add_f32_e32 v95, v95, v94
	v_pk_mul_f32 v[86:87], v[82:83], v[86:87] op_sel_hi:[0,1]
	v_cvt_pk_bf16_f32 v85, v86, v87
	ds_write_b64 v83, v[84:85] offset:16
	v_add_f32_e32 v84, v154, v151
	v_add_f32_e32 v85, v90, v151
	ds_read_u16 v86, v97 offset:21760
	ds_read_u16 v87, v97 offset:22032
	v_mul_f32_e32 v84, 0xbfb8aa3b, v84
	v_mul_f32_e32 v85, 0xbfb8aa3b, v85
	v_exp_f32_e32 v84, v84
	v_exp_f32_e32 v85, v85
	s_waitcnt lgkmcnt(0)
	v_lshlrev_b32_e32 v87, 16, v87
	v_lshlrev_b32_e32 v86, 16, v86
	v_add_f32_e32 v96, v96, v95
	v_pk_mul_f32 v[84:85], v[84:85], v[86:87]
	v_add_f32_e32 v87, v92, v151
	v_pk_mul_f32 v[84:85], v[82:83], v[84:85] op_sel_hi:[0,1]
	v_cvt_pk_bf16_f32 v84, v84, v85
	v_add_f32_e32 v85, v91, v151
	v_mul_f32_e32 v85, 0xbfb8aa3b, v85
	v_exp_f32_e32 v86, v85
	v_mul_f32_e32 v85, 0xbfb8aa3b, v87
	v_exp_f32_e32 v87, v85
	ds_read_u16 v85, v97 offset:22304
	ds_read_u16 v88, v97 offset:22576
	s_add_u32 s30, s68, s53
	s_addc_u32 s31, s69, s54
	s_waitcnt lgkmcnt(0)
	v_lshlrev_b32_e32 v89, 16, v88
	v_lshlrev_b32_e32 v88, 16, v85
	v_pk_mul_f32 v[86:87], v[86:87], v[88:89]
	s_nop 0
	v_pk_mul_f32 v[86:87], v[82:83], v[86:87] op_sel_hi:[0,1]
	v_cvt_pk_bf16_f32 v85, v86, v87
	ds_write_b64 v83, v[84:85] offset:32
	v_add_f32_e32 v84, v93, v151
	v_add_f32_e32 v85, v94, v151
	ds_read_u16 v86, v97 offset:23936
	ds_read_u16 v87, v97 offset:24208
	v_mul_f32_e32 v84, 0xbfb8aa3b, v84
	v_mul_f32_e32 v85, 0xbfb8aa3b, v85
	v_exp_f32_e32 v84, v84
	v_exp_f32_e32 v85, v85
	s_waitcnt lgkmcnt(0)
	v_lshlrev_b32_e32 v87, 16, v87
	v_lshlrev_b32_e32 v86, 16, v86
	v_pk_mul_f32 v[84:85], v[84:85], v[86:87]
	s_nop 0
	v_pk_mul_f32 v[84:85], v[82:83], v[84:85] op_sel_hi:[0,1]
	v_cvt_pk_bf16_f32 v84, v84, v85
	v_add_f32_e32 v85, v95, v151
	v_add_f32_e32 v87, v96, v151
	v_mul_f32_e32 v85, 0xbfb8aa3b, v85
	v_exp_f32_e32 v86, v85
	v_mul_f32_e32 v85, 0xbfb8aa3b, v87
	v_exp_f32_e32 v87, v85
	ds_read_u16 v85, v97 offset:24480
	ds_read_u16 v88, v97 offset:24752
	s_waitcnt lgkmcnt(0)
	v_lshlrev_b32_e32 v89, 16, v88
	v_lshlrev_b32_e32 v88, 16, v85
	v_pk_mul_f32 v[86:87], v[86:87], v[88:89]
	s_nop 0
	v_pk_mul_f32 v[86:87], v[82:83], v[86:87] op_sel_hi:[0,1]
	v_cvt_pk_bf16_f32 v85, v86, v87
	v_mov_b32_e32 v82, v128
	ds_write_b64 v83, v[84:85] offset:48
	v_mov_b32_e32 v86, v0
	s_waitcnt vmcnt(3)
	ds_write_b128 v82, v[98:101]
	s_waitcnt vmcnt(2)
	ds_write_b128 v82, v[102:105] offset:9216
	s_waitcnt vmcnt(1)
	ds_write_b128 v82, v[106:109] offset:18432
	s_waitcnt vmcnt(0)
	ds_write_b128 v82, v[110:113] offset:27648
	v_mov_b32_e32 v110, v129
	v_ashrrev_i32_e32 v82, 2, v86
	v_lshlrev_b32_e32 v83, 2, v86
	v_min_i32_e32 v82, 63, v82
	v_and_b32_e32 v83, 12, v83
	v_lshl_or_b32 v116, v82, 4, v83
	v_ashrrev_i32_e32 v90, 4, v86
	v_lshlrev_b32_e32 v86, 3, v86
	v_lshl_add_u64 v[82:83], v[116:117], 2, s[30:31]
	v_and_b32_e32 v91, 0x78, v86
	v_min_i32_e32 v86, 63, v90
	s_add_u32 s30, s68, s34
	v_min_i32_e32 v90, 31, v90
	v_lshl_or_b32 v116, v86, 10, v91
	s_addc_u32 s31, s69, s35
	v_lshl_or_b32 v90, v90, 10, v91
	v_lshl_add_u64 v[86:87], v[116:117], 1, s[30:31]
	v_add_u32_e32 v116, 0x8000, v90
	v_lshl_add_u64 v[90:91], v[116:117], 1, s[30:31]
	global_load_dwordx4 v[82:85], v[82:83], off
	v_mov_b32_e32 v100, v135
	global_load_dwordx4 v[86:89], v[86:87], off
	v_mov_b32_e32 v111, v131
	global_load_dwordx4 v[90:93], v[90:91], off
	s_waitcnt lgkmcnt(0)
	s_barrier
; #define LAS __attribute__((address_space(3)))
; template <class T> __device__ __forceinline__ LAS T* opq(LAS T* p) { unsigned a = __builtin_bit_cast(unsigned, p); asm volatile("" : "+v"(a)); return __builtin_bit_cast(LAS T*, a); }
; #define MFMA32(a, b, c) __builtin_amdgcn_mfma_f32_32x32x16_bf16((a), (b), (c), 0, 0, 0)
; __device__ __forceinline__ s16x4 tr16(const LAS bf16_t* p) { return __builtin_bit_cast(s16x4, __builtin_amdgcn_ds_read_tr16_b64_v4i16((LAS v4i16_t*)p)); }
; __device__ __forceinline__ s16x4 tr16(const LAS bf16_t* p) { return __builtin_bit_cast(s16x4, __builtin_amdgcn_ds_read_tr16_b64_v4i16((LAS v4i16_t*)p)); }
; template <bool FULL, bool PARTIAL  > ...
;     ...
;         const LAS bf16_t* kdt_r = opq(KdT + r * TST + 8 * h);
;         if (!FULL) {
;             const LAS bf16_t* vt_r2 = opq(VS + (8 * h + ((lane & 15) >> 2)) * VST + 32 * w + 16 * ((lane >> 4) & 1) + 4 * (lane & 3));
; #pragma unroll
;             for (int s4 = 0; s4 < 4; ++s4) { const s16x4 vlo = tr16(vt_r2 + (16 * s4) * VST), vhi = tr16(vt_r2 + (16 * s4 + 4) * VST); vfr[s4] = __builtin_shufflevector(vlo, vhi, 0, 1, 2, 3, 4, 5, 6, 7); }
;         }
;         const LAS float* eb_r = opq(EB + 4 * h);
; #pragma unroll
;         for (int kb = 0; kb < 4; ++kb) {
; #pragma unroll
;             for (int q4 = 0; q4 < 4; ++q4) { const f32x4 e = *(const LAS f32x4*)(eb_r + 32 * kb + 8 * q4);
; #pragma unroll
;                 for (int e2 = 0; e2 < 4; ++e2) Sacc[kb][4 * q4 + e2] *= e[e2]; }
; #pragma unroll
;             for (int s = 0; s < 4; ++s) {
;                 const bf16x8 ka = *(const LAS bf16x8*)(kdt_r + (32 * kb) * TST + 16 * s);
;                 Sacc[kb] = MFMA32(ka, vfr[s], Sacc[kb]);
;             }
;             __builtin_amdgcn_sched_barrier(0);
;         }
	ds_read_b64_tr_b16 v[94:95], v100
	ds_read_b64_tr_b16 v[96:97], v100 offset:2304
	ds_read_b64_tr_b16 v[102:103], v100 offset:9216
	ds_read_b64_tr_b16 v[104:105], v100 offset:11520
	ds_read_b64_tr_b16 v[106:107], v100 offset:18432
	ds_read_b64_tr_b16 v[108:109], v100 offset:20736
	ds_read_b64_tr_b16 v[98:99], v100 offset:27648
	ds_read_b64_tr_b16 v[100:101], v100 offset:29952
	ds_read_b128 v[150:153], v111
	ds_read_b128 v[154:157], v111 offset:32
	ds_read_b128 v[158:161], v111 offset:64
	ds_read_b128 v[162:165], v111 offset:96
	s_waitcnt lgkmcnt(3)
	v_pk_mul_f32 v[52:53], v[52:53], v[152:153]
	s_waitcnt lgkmcnt(2)
	v_pk_mul_f32 v[56:57], v[56:57], v[156:157]
	v_pk_mul_f32 v[54:55], v[54:55], v[154:155]
	v_pk_mul_f32 v[50:51], v[50:51], v[150:151]
	ds_read_b128 v[150:153], v110
	ds_read_b128 v[154:157], v110 offset:32
	s_waitcnt lgkmcnt(2)
	v_pk_mul_f32 v[64:65], v[64:65], v[164:165]
	v_pk_mul_f32 v[60:61], v[60:61], v[160:161]
	v_pk_mul_f32 v[62:63], v[62:63], v[162:163]
	v_pk_mul_f32 v[58:59], v[58:59], v[158:159]
	ds_read_b128 v[158:161], v110 offset:64
	ds_read_b128 v[162:165], v110 offset:96
	s_waitcnt lgkmcnt(3)
	s_nop 0
	v_mfma_f32_32x32x16_bf16 v[50:65], v[150:153], v[94:97], v[50:65]
	s_waitcnt lgkmcnt(2)
	v_mfma_f32_32x32x16_bf16 v[50:65], v[154:157], v[102:105], v[50:65]
	s_waitcnt lgkmcnt(1)
	v_mfma_f32_32x32x16_bf16 v[50:65], v[158:161], v[106:109], v[50:65]
	s_waitcnt lgkmcnt(0)
	v_mfma_f32_32x32x16_bf16 v[50:65], v[162:165], v[98:101], v[50:65]
	ds_read_b128 v[150:153], v111 offset:128
	ds_read_b128 v[154:157], v111 offset:160
	ds_read_b128 v[158:161], v111 offset:192
	ds_read_b128 v[162:165], v111 offset:224
	s_waitcnt lgkmcnt(3)
	v_pk_mul_f32 v[36:37], v[36:37], v[152:153]
	s_waitcnt lgkmcnt(2)
	v_pk_mul_f32 v[40:41], v[40:41], v[156:157]
	v_pk_mul_f32 v[38:39], v[38:39], v[154:155]
	v_pk_mul_f32 v[34:35], v[34:35], v[150:151]
	ds_read_b128 v[150:153], v110 offset:4608
	ds_read_b128 v[154:157], v110 offset:4640
	s_waitcnt lgkmcnt(2)
	v_pk_mul_f32 v[48:49], v[48:49], v[164:165]
	v_pk_mul_f32 v[44:45], v[44:45], v[160:161]
	v_pk_mul_f32 v[46:47], v[46:47], v[162:163]
	v_pk_mul_f32 v[42:43], v[42:43], v[158:159]
	ds_read_b128 v[158:161], v110 offset:4672
	ds_read_b128 v[162:165], v110 offset:4704
	s_waitcnt lgkmcnt(3)
	s_nop 0
	v_mfma_f32_32x32x16_bf16 v[34:49], v[150:153], v[94:97], v[34:49]
	s_waitcnt lgkmcnt(2)
	v_mfma_f32_32x32x16_bf16 v[34:49], v[154:157], v[102:105], v[34:49]
	s_waitcnt lgkmcnt(1)
	v_mfma_f32_32x32x16_bf16 v[34:49], v[158:161], v[106:109], v[34:49]
	s_waitcnt lgkmcnt(0)
	v_mfma_f32_32x32x16_bf16 v[34:49], v[162:165], v[98:101], v[34:49]
	ds_read_b128 v[150:153], v111 offset:256
	ds_read_b128 v[154:157], v111 offset:288
	ds_read_b128 v[158:161], v111 offset:320
	ds_read_b128 v[162:165], v111 offset:352
	s_waitcnt lgkmcnt(3)
	v_pk_mul_f32 v[20:21], v[20:21], v[152:153]
	s_waitcnt lgkmcnt(2)
	v_pk_mul_f32 v[24:25], v[24:25], v[156:157]
	v_pk_mul_f32 v[22:23], v[22:23], v[154:155]
	v_pk_mul_f32 v[18:19], v[18:19], v[150:151]
	ds_read_b128 v[150:153], v110 offset:9216
	ds_read_b128 v[154:157], v110 offset:9248
	s_waitcnt lgkmcnt(2)
	v_pk_mul_f32 v[32:33], v[32:33], v[164:165]
	v_pk_mul_f32 v[28:29], v[28:29], v[160:161]
	v_pk_mul_f32 v[30:31], v[30:31], v[162:163]
	v_pk_mul_f32 v[26:27], v[26:27], v[158:159]
	ds_read_b128 v[158:161], v110 offset:9280
	ds_read_b128 v[162:165], v110 offset:9312
	s_waitcnt lgkmcnt(3)
	s_nop 0
	v_mfma_f32_32x32x16_bf16 v[18:33], v[150:153], v[94:97], v[18:33]
	s_waitcnt lgkmcnt(2)
	v_mfma_f32_32x32x16_bf16 v[18:33], v[154:157], v[102:105], v[18:33]
	s_waitcnt lgkmcnt(1)
	v_mfma_f32_32x32x16_bf16 v[18:33], v[158:161], v[106:109], v[18:33]
	s_waitcnt lgkmcnt(0)
	v_mfma_f32_32x32x16_bf16 v[18:33], v[162:165], v[98:101], v[18:33]
	ds_read_b128 v[150:153], v111 offset:384
	ds_read_b128 v[154:157], v111 offset:416
	ds_read_b128 v[158:161], v111 offset:448
	ds_read_b128 v[162:165], v111 offset:480
	s_waitcnt lgkmcnt(3)
	v_pk_mul_f32 v[4:5], v[4:5], v[152:153]
	s_waitcnt lgkmcnt(2)
	v_pk_mul_f32 v[8:9], v[8:9], v[156:157]
	v_pk_mul_f32 v[6:7], v[6:7], v[154:155]
	v_pk_mul_f32 v[2:3], v[2:3], v[150:151]
	ds_read_b128 v[150:153], v110 offset:13824
	ds_read_b128 v[154:157], v110 offset:13856
	s_waitcnt lgkmcnt(2)
	v_pk_mul_f32 v[16:17], v[16:17], v[164:165]
	v_pk_mul_f32 v[12:13], v[12:13], v[160:161]
	v_pk_mul_f32 v[14:15], v[14:15], v[162:163]
	v_pk_mul_f32 v[10:11], v[10:11], v[158:159]
	ds_read_b128 v[158:161], v110 offset:13888
	ds_read_b128 v[162:165], v110 offset:13920
	s_waitcnt lgkmcnt(3)
	s_nop 0
	v_mfma_f32_32x32x16_bf16 v[2:17], v[150:153], v[94:97], v[2:17]
	s_waitcnt lgkmcnt(2)
	v_mfma_f32_32x32x16_bf16 v[2:17], v[154:157], v[102:105], v[2:17]
	s_waitcnt lgkmcnt(1)
	v_mfma_f32_32x32x16_bf16 v[2:17], v[158:161], v[106:109], v[2:17]
	s_waitcnt lgkmcnt(0)
	v_mfma_f32_32x32x16_bf16 v[2:17], v[162:165], v[98:101], v[2:17]
	s_add_u32 s45, s45, 0x20000
	s_addc_u32 s52, s52, 0
	s_add_u32 s34, s34, 0x20000
	s_addc_u32 s35, s35, 0
	s_add_u32 s53, s53, 0x1000
	s_addc_u32 s54, s54, 0
	s_add_i32 s55, s55, -1
	s_cmp_eq_u32 s55, 0
	s_barrier
	s_cbranch_scc1 .LBB0_1050
